# speedup vs baseline: 1.0116x; 1.0032x over previous
; template <int A0, int A1, int B0, int B1, bool LOC> ...
;     ...
;     float ps = 0.f;
; #pragma unroll
;     for (int i = 0; i < 16; ++i) { if (i >= A0 && i < A1) { s0[i] = __builtin_amdgcn_exp2f(s0[i] - mn); ps += s0[i]; } else s0[i] = 0.f; }
; #pragma unroll
;     for (int i = 0; i < 16; ++i) { if (i >= B0 && i < B1) { s1v[i] = __builtin_amdgcn_exp2f(s1v[i] - mn); ps += s1v[i]; } else s1v[i] = 0.f; }
;     lsum += ps;
.LBB0_499:
	v_pk_add_f32 v[52:53], v[52:53], v[194:195] op_sel:[0,1] op_sel_hi:[1,1] neg_lo:[0,1] neg_hi:[0,1]
	v_pk_add_f32 v[54:55], v[54:55], v[194:195] op_sel:[0,1] op_sel_hi:[1,1] neg_lo:[0,1] neg_hi:[0,1]
	v_pk_add_f32 v[56:57], v[56:57], v[194:195] op_sel:[0,1] op_sel_hi:[1,1] neg_lo:[0,1] neg_hi:[0,1]
	v_pk_add_f32 v[58:59], v[58:59], v[194:195] op_sel:[0,1] op_sel_hi:[1,1] neg_lo:[0,1] neg_hi:[0,1]
	v_pk_add_f32 v[60:61], v[60:61], v[194:195] op_sel:[0,1] op_sel_hi:[1,1] neg_lo:[0,1] neg_hi:[0,1]
	v_pk_add_f32 v[62:63], v[62:63], v[194:195] op_sel:[0,1] op_sel_hi:[1,1] neg_lo:[0,1] neg_hi:[0,1]
	v_pk_add_f32 v[64:65], v[64:65], v[194:195] op_sel:[0,1] op_sel_hi:[1,1] neg_lo:[0,1] neg_hi:[0,1]
	v_pk_add_f32 v[66:67], v[66:67], v[194:195] op_sel:[0,1] op_sel_hi:[1,1] neg_lo:[0,1] neg_hi:[0,1]
	v_pk_add_f32 v[36:37], v[36:37], v[194:195] op_sel:[0,1] op_sel_hi:[1,1] neg_lo:[0,1] neg_hi:[0,1]
	v_pk_add_f32 v[38:39], v[38:39], v[194:195] op_sel:[0,1] op_sel_hi:[1,1] neg_lo:[0,1] neg_hi:[0,1]
	v_pk_add_f32 v[40:41], v[40:41], v[194:195] op_sel:[0,1] op_sel_hi:[1,1] neg_lo:[0,1] neg_hi:[0,1]
	v_pk_add_f32 v[42:43], v[42:43], v[194:195] op_sel:[0,1] op_sel_hi:[1,1] neg_lo:[0,1] neg_hi:[0,1]
	v_pk_add_f32 v[44:45], v[44:45], v[194:195] op_sel:[0,1] op_sel_hi:[1,1] neg_lo:[0,1] neg_hi:[0,1]
	v_pk_add_f32 v[46:47], v[46:47], v[194:195] op_sel:[0,1] op_sel_hi:[1,1] neg_lo:[0,1] neg_hi:[0,1]
	v_pk_add_f32 v[48:49], v[48:49], v[194:195] op_sel:[0,1] op_sel_hi:[1,1] neg_lo:[0,1] neg_hi:[0,1]
	v_pk_add_f32 v[50:51], v[50:51], v[194:195] op_sel:[0,1] op_sel_hi:[1,1] neg_lo:[0,1] neg_hi:[0,1]
	v_exp_f32_e32 v52, v52
	v_exp_f32_e32 v53, v53
	v_exp_f32_e32 v54, v54
	v_exp_f32_e32 v55, v55
	v_exp_f32_e32 v56, v56
	v_exp_f32_e32 v57, v57
	v_pk_add_f32 v[80:81], v[52:53], v[54:55]
	v_exp_f32_e32 v58, v58
	v_exp_f32_e32 v59, v59
	v_pk_add_f32 v[80:81], v[80:81], v[56:57]
	v_exp_f32_e32 v60, v60
	v_exp_f32_e32 v61, v61
	v_pk_add_f32 v[80:81], v[80:81], v[58:59]
	v_exp_f32_e32 v62, v62
	v_exp_f32_e32 v63, v63
	v_pk_add_f32 v[80:81], v[80:81], v[60:61]
	v_exp_f32_e32 v64, v64
	v_exp_f32_e32 v65, v65
	v_pk_add_f32 v[80:81], v[80:81], v[62:63]
	v_exp_f32_e32 v66, v66
	v_exp_f32_e32 v67, v67
	v_pk_add_f32 v[80:81], v[80:81], v[64:65]
	v_exp_f32_e32 v36, v36
	v_exp_f32_e32 v37, v37
	v_pk_add_f32 v[80:81], v[80:81], v[66:67]
	v_exp_f32_e32 v38, v38
	v_exp_f32_e32 v39, v39
	v_pk_add_f32 v[80:81], v[80:81], v[36:37]
	v_exp_f32_e32 v40, v40
	v_exp_f32_e32 v41, v41
	v_pk_add_f32 v[80:81], v[80:81], v[38:39]
	v_exp_f32_e32 v42, v42
	v_exp_f32_e32 v43, v43
	v_pk_add_f32 v[80:81], v[80:81], v[40:41]
	v_exp_f32_e32 v44, v44
	v_exp_f32_e32 v45, v45
	v_pk_add_f32 v[80:81], v[80:81], v[42:43]
	v_exp_f32_e32 v46, v46
	v_exp_f32_e32 v47, v47
	v_pk_add_f32 v[80:81], v[80:81], v[44:45]
	v_exp_f32_e32 v48, v48
	v_exp_f32_e32 v49, v49
	v_pk_add_f32 v[80:81], v[80:81], v[46:47]
	v_exp_f32_e32 v50, v50
	v_exp_f32_e32 v51, v51
	v_pk_add_f32 v[80:81], v[80:81], v[48:49]
	v_add_u32_e32 v0, v183, v184
	v_add_u32_e32 v1, v183, v185
	v_pk_add_f32 v[80:81], v[80:81], v[50:51]
	s_nop 0
	v_add_f32_e32 v3, v80, v81
	v_add_f32_e32 v196, v3, v141
	ds_read_b64_tr_b16 v[72:73], v0 offset:32768
	ds_read_b64_tr_b16 v[74:75], v0 offset:33792
	ds_read_b64_tr_b16 v[76:77], v1 offset:32768
	ds_read_b64_tr_b16 v[78:79], v1 offset:33792
	v_cvt_pk_bf16_f32 v68, v52, v53
	v_cvt_pk_bf16_f32 v69, v54, v55
	v_cvt_pk_bf16_f32 v70, v56, v57
	v_cvt_pk_bf16_f32 v71, v58, v59
	s_waitcnt lgkmcnt(0)
	s_nop 0
	v_mfma_f32_32x32x16_bf16 v[20:35], v[72:75], v[68:71], v[20:35]
	v_mfma_f32_32x32x16_bf16 v[4:19], v[76:79], v[68:71], v[4:19]
	ds_read_b64_tr_b16 v[72:73], v0 offset:34816
	ds_read_b64_tr_b16 v[74:75], v0 offset:35840
	ds_read_b64_tr_b16 v[76:77], v1 offset:34816
	ds_read_b64_tr_b16 v[78:79], v1 offset:35840
	v_cvt_pk_bf16_f32 v68, v60, v61
	v_cvt_pk_bf16_f32 v69, v62, v63
	v_cvt_pk_bf16_f32 v70, v64, v65
	v_cvt_pk_bf16_f32 v71, v66, v67
	s_waitcnt lgkmcnt(0)
	s_nop 0
	v_mfma_f32_32x32x16_bf16 v[20:35], v[72:75], v[68:71], v[20:35]
	v_mfma_f32_32x32x16_bf16 v[4:19], v[76:79], v[68:71], v[4:19]
	ds_read_b64_tr_b16 v[72:73], v0 offset:36864
	ds_read_b64_tr_b16 v[74:75], v0 offset:37888
	ds_read_b64_tr_b16 v[76:77], v1 offset:36864
	ds_read_b64_tr_b16 v[78:79], v1 offset:37888
	v_cvt_pk_bf16_f32 v68, v36, v37
	v_cvt_pk_bf16_f32 v69, v38, v39
	v_cvt_pk_bf16_f32 v70, v40, v41
	v_cvt_pk_bf16_f32 v71, v42, v43
	s_waitcnt lgkmcnt(0)
	s_nop 0
	v_mfma_f32_32x32x16_bf16 v[20:35], v[72:75], v[68:71], v[20:35]
	v_mfma_f32_32x32x16_bf16 v[4:19], v[76:79], v[68:71], v[4:19]
	ds_read_b64_tr_b16 v[72:73], v0 offset:38912
	ds_read_b64_tr_b16 v[74:75], v0 offset:39936
	ds_read_b64_tr_b16 v[76:77], v1 offset:38912
	ds_read_b64_tr_b16 v[78:79], v1 offset:39936
	v_cvt_pk_bf16_f32 v68, v44, v45
	v_cvt_pk_bf16_f32 v69, v46, v47
	v_cvt_pk_bf16_f32 v70, v48, v49
	v_cvt_pk_bf16_f32 v71, v50, v51
	s_waitcnt lgkmcnt(0)
	s_nop 0
	v_mfma_f32_32x32x16_bf16 v[20:35], v[72:75], v[68:71], v[20:35]
	v_mfma_f32_32x32x16_bf16 v[4:19], v[76:79], v[68:71], v[4:19]

; template <int A0, int A1, int B0, int B1, bool LOC> ...
;     ...
;     float ps = 0.f;
; #pragma unroll
;     for (int i = 0; i < 16; ++i) { if (i >= A0 && i < A1) { s0[i] = __builtin_amdgcn_exp2f(s0[i] - mn); ps += s0[i]; } else s0[i] = 0.f; }
; #pragma unroll
;     for (int i = 0; i < 16; ++i) { if (i >= B0 && i < B1) { s1v[i] = __builtin_amdgcn_exp2f(s1v[i] - mn); ps += s1v[i]; } else s1v[i] = 0.f; }
;     lsum += ps;
.LBB0_523:
	v_pk_add_f32 v[52:53], v[52:53], v[194:195] op_sel:[0,1] op_sel_hi:[1,1] neg_lo:[0,1] neg_hi:[0,1]
	v_pk_add_f32 v[54:55], v[54:55], v[194:195] op_sel:[0,1] op_sel_hi:[1,1] neg_lo:[0,1] neg_hi:[0,1]
	v_pk_add_f32 v[56:57], v[56:57], v[194:195] op_sel:[0,1] op_sel_hi:[1,1] neg_lo:[0,1] neg_hi:[0,1]
	v_pk_add_f32 v[58:59], v[58:59], v[194:195] op_sel:[0,1] op_sel_hi:[1,1] neg_lo:[0,1] neg_hi:[0,1]
	v_pk_add_f32 v[60:61], v[60:61], v[194:195] op_sel:[0,1] op_sel_hi:[1,1] neg_lo:[0,1] neg_hi:[0,1]
	v_pk_add_f32 v[62:63], v[62:63], v[194:195] op_sel:[0,1] op_sel_hi:[1,1] neg_lo:[0,1] neg_hi:[0,1]
	v_pk_add_f32 v[64:65], v[64:65], v[194:195] op_sel:[0,1] op_sel_hi:[1,1] neg_lo:[0,1] neg_hi:[0,1]
	v_pk_add_f32 v[66:67], v[66:67], v[194:195] op_sel:[0,1] op_sel_hi:[1,1] neg_lo:[0,1] neg_hi:[0,1]
	v_pk_add_f32 v[36:37], v[36:37], v[194:195] op_sel:[0,1] op_sel_hi:[1,1] neg_lo:[0,1] neg_hi:[0,1]
	v_pk_add_f32 v[38:39], v[38:39], v[194:195] op_sel:[0,1] op_sel_hi:[1,1] neg_lo:[0,1] neg_hi:[0,1]
	v_pk_add_f32 v[40:41], v[40:41], v[194:195] op_sel:[0,1] op_sel_hi:[1,1] neg_lo:[0,1] neg_hi:[0,1]
	v_pk_add_f32 v[42:43], v[42:43], v[194:195] op_sel:[0,1] op_sel_hi:[1,1] neg_lo:[0,1] neg_hi:[0,1]
	v_pk_add_f32 v[44:45], v[44:45], v[194:195] op_sel:[0,1] op_sel_hi:[1,1] neg_lo:[0,1] neg_hi:[0,1]
	v_pk_add_f32 v[46:47], v[46:47], v[194:195] op_sel:[0,1] op_sel_hi:[1,1] neg_lo:[0,1] neg_hi:[0,1]
	v_pk_add_f32 v[48:49], v[48:49], v[194:195] op_sel:[0,1] op_sel_hi:[1,1] neg_lo:[0,1] neg_hi:[0,1]
	v_pk_add_f32 v[50:51], v[50:51], v[194:195] op_sel:[0,1] op_sel_hi:[1,1] neg_lo:[0,1] neg_hi:[0,1]
	v_exp_f32_e32 v52, v52
	v_exp_f32_e32 v53, v53
	v_exp_f32_e32 v54, v54
	v_exp_f32_e32 v55, v55
	v_exp_f32_e32 v56, v56
	v_exp_f32_e32 v57, v57
	v_pk_add_f32 v[80:81], v[52:53], v[54:55]
	v_exp_f32_e32 v58, v58
	v_exp_f32_e32 v59, v59
	v_pk_add_f32 v[80:81], v[80:81], v[56:57]
	v_exp_f32_e32 v60, v60
	v_exp_f32_e32 v61, v61
	v_pk_add_f32 v[80:81], v[80:81], v[58:59]
	v_exp_f32_e32 v62, v62
	v_exp_f32_e32 v63, v63
	v_pk_add_f32 v[80:81], v[80:81], v[60:61]
	v_exp_f32_e32 v64, v64
	v_exp_f32_e32 v65, v65
	v_pk_add_f32 v[80:81], v[80:81], v[62:63]
	v_exp_f32_e32 v66, v66
	v_exp_f32_e32 v67, v67
	v_pk_add_f32 v[80:81], v[80:81], v[64:65]
	v_exp_f32_e32 v36, v36
	v_exp_f32_e32 v37, v37
	v_pk_add_f32 v[80:81], v[80:81], v[66:67]
	v_exp_f32_e32 v38, v38
	v_exp_f32_e32 v39, v39
	v_pk_add_f32 v[80:81], v[80:81], v[36:37]
	v_exp_f32_e32 v40, v40
	v_exp_f32_e32 v41, v41
	v_pk_add_f32 v[80:81], v[80:81], v[38:39]
	v_exp_f32_e32 v42, v42
	v_exp_f32_e32 v43, v43
	v_pk_add_f32 v[80:81], v[80:81], v[40:41]
	v_exp_f32_e32 v44, v44
	v_exp_f32_e32 v45, v45
	v_pk_add_f32 v[80:81], v[80:81], v[42:43]
	v_exp_f32_e32 v46, v46
	v_exp_f32_e32 v47, v47
	v_pk_add_f32 v[80:81], v[80:81], v[44:45]
	v_exp_f32_e32 v48, v48
	v_exp_f32_e32 v49, v49
	v_pk_add_f32 v[80:81], v[80:81], v[46:47]
	v_exp_f32_e32 v50, v50
	v_exp_f32_e32 v51, v51
	v_pk_add_f32 v[80:81], v[80:81], v[48:49]
	v_add_u32_e32 v0, v183, v184
	v_add_u32_e32 v1, v183, v185
	v_pk_add_f32 v[80:81], v[80:81], v[50:51]
	s_nop 0
	v_add_f32_e32 v3, v80, v81
	v_add_f32_e32 v196, v3, v141
	ds_read_b64_tr_b16 v[72:73], v0 offset:40960
	ds_read_b64_tr_b16 v[74:75], v0 offset:41984
	ds_read_b64_tr_b16 v[76:77], v1 offset:40960
	ds_read_b64_tr_b16 v[78:79], v1 offset:41984
	v_cvt_pk_bf16_f32 v68, v52, v53
	v_cvt_pk_bf16_f32 v69, v54, v55
	v_cvt_pk_bf16_f32 v70, v56, v57
	v_cvt_pk_bf16_f32 v71, v58, v59
	s_waitcnt lgkmcnt(0)
	s_nop 0
	v_mfma_f32_32x32x16_bf16 v[20:35], v[72:75], v[68:71], v[20:35]
	v_mfma_f32_32x32x16_bf16 v[4:19], v[76:79], v[68:71], v[4:19]
	ds_read_b64_tr_b16 v[72:73], v0 offset:43008
	ds_read_b64_tr_b16 v[74:75], v0 offset:44032
	ds_read_b64_tr_b16 v[76:77], v1 offset:43008
	ds_read_b64_tr_b16 v[78:79], v1 offset:44032
	v_cvt_pk_bf16_f32 v68, v60, v61
	v_cvt_pk_bf16_f32 v69, v62, v63
	v_cvt_pk_bf16_f32 v70, v64, v65
	v_cvt_pk_bf16_f32 v71, v66, v67
	s_waitcnt lgkmcnt(0)
	s_nop 0
	v_mfma_f32_32x32x16_bf16 v[20:35], v[72:75], v[68:71], v[20:35]
	v_mfma_f32_32x32x16_bf16 v[4:19], v[76:79], v[68:71], v[4:19]
	ds_read_b64_tr_b16 v[72:73], v0 offset:45056
	ds_read_b64_tr_b16 v[74:75], v0 offset:46080
	ds_read_b64_tr_b16 v[76:77], v1 offset:45056
	ds_read_b64_tr_b16 v[78:79], v1 offset:46080
	v_cvt_pk_bf16_f32 v68, v36, v37
	v_cvt_pk_bf16_f32 v69, v38, v39
	v_cvt_pk_bf16_f32 v70, v40, v41
	v_cvt_pk_bf16_f32 v71, v42, v43
	s_waitcnt lgkmcnt(0)
	s_nop 0
	v_mfma_f32_32x32x16_bf16 v[20:35], v[72:75], v[68:71], v[20:35]
	v_mfma_f32_32x32x16_bf16 v[4:19], v[76:79], v[68:71], v[4:19]
	ds_read_b64_tr_b16 v[72:73], v0 offset:47104
	ds_read_b64_tr_b16 v[74:75], v0 offset:48128
	ds_read_b64_tr_b16 v[76:77], v1 offset:47104
	ds_read_b64_tr_b16 v[78:79], v1 offset:48128
	v_cvt_pk_bf16_f32 v68, v44, v45
	v_cvt_pk_bf16_f32 v69, v46, v47
	v_cvt_pk_bf16_f32 v70, v48, v49
	v_cvt_pk_bf16_f32 v71, v50, v51
	s_waitcnt lgkmcnt(0)
	s_nop 0
	v_mfma_f32_32x32x16_bf16 v[20:35], v[72:75], v[68:71], v[20:35]
	v_mfma_f32_32x32x16_bf16 v[4:19], v[76:79], v[68:71], v[4:19]
